# attention: online-softmax rescale only when row max rises by more than 8 (log2 units); skips O*=alpha in most steps
# speedup vs baseline: 1.0132x; 1.0132x over previous
; template <int DQ, int TYPE>
; __device__ __forceinline__ void attn_item(PP p, int layer, int b, int h, int qt, char* lds, const int tid_, unsigned* next_ctr, volatile XLAS unsigned* slot) {
;     ...
;         if (!skip) {
;             const bf16_t* Ks = (const bf16_t*)(lds + buf * STAGE); const bf16_t* Vt = (const bf16_t*)(lds + buf * STAGE + KBYTES);
;             f32x16 sacc;
; #pragma unroll
;             for (int i = 0; i < 16; ++i) sacc[i] = 0.f;
;             const bf16_t* kb_ = Ks + (32 * kh + r) * KLD + 8 * hh;
;             bf16x8 kf[2][GK];
; #pragma unroll
;             for (int i = 0; i < GK; ++i) kf[0][i] = *(const bf16x8*)(kb_ + 16 * i);
; #pragma unroll
;             for (int g = 0; g < NG; ++g) {
;                 if (g + 1 < NG) {
; #pragma unroll
;                     for (int i = 0; i < GK; ++i) kf[(g + 1) & 1][i] = *(const bf16x8*)(kb_ + 16 * ((g + 1) * GK + i));
;                 }
;                 __builtin_amdgcn_sched_barrier(0);
; #pragma unroll
;                 for (int i = 0; i < GK; ++i) sacc = __builtin_amdgcn_mfma_f32_32x32x16_bf16(kf[g & 1][i], qf[g * GK + i], sacc, 0, 0, 0);
;                 __builtin_amdgcn_sched_barrier(0);
;             }
;             const bf16_t* vb0 = Vt + r * VLD + 32 * kh + 4 * hh;
;             u32x2 vf[2][4][2];
; #pragma unroll
;             for (int md = 0; md < 4; ++md) { vf[0][md][0] = *(const u32x2*)(vb0 + md * 32 * VLD); vf[0][md][1] = *(const u32x2*)(vb0 + md * 32 * VLD + 8); }
;             if (mode != 0) {
;                 const bool selbit = (qmask >> (j >> 2)) & 1u;
; #pragma unroll
;                 for (int i = 0; i < 16; ++i) {
;                     const int kpos = kbase_pos + 8 * (i >> 2) + 4 * hh + (i & 3);
;                     const int dd = qpos - kpos;
;                     bool ok;
;                     if (mode == 1) ok = dd >= 0; else if (mode == 2) ok = (dd >= 0 && dd < 128); else ok = selbit;
;                     if (!ok) sacc[i] = -INFINITY;
;                 }
;             }
;             float mx = fmaxf(sacc[0], sacc[1]);
; #pragma unroll
;             for (int i = 2; i < 16; i += 2) mx = fmaxf(mx, fmaxf(sacc[i], sacc[i + 1]));
;             mx *= c;
;             mx = fmaxf(mx, __shfl_xor(mx, 32));
;             const float m_old_ = m_run;
;             const float mnew = fmaxf(m_run, mx);
;             const float alpha = fast_exp2(m_run - mnew);
.LBB0_408:
	s_and_b32 s60, s12, 1
	s_cmp_gt_i32 s59, s57
	s_cselect_b64 s[62:63], -1, 0
	s_add_i32 s61, s59, 31
	s_cmp_le_i32 s61, s58
	s_cselect_b64 s[64:65], -1, 0
	s_or_b64 s[62:63], s[64:65], s[62:63]
	s_and_b64 vcc, exec, s[62:63]
	s_cbranch_vccnz .LBB0_412
	s_mul_i32 s61, s60, 0x8800
	s_add_i32 s61, s61, 16
	v_add3_u32 v0, s61, v163, v167
	ds_read_b128 v[2:5], v0
	ds_read_b128 v[6:9], v0 offset:32
	ds_read_b128 v[10:13], v0 offset:64
	ds_read_b128 v[170:173], v0 offset:96
	ds_read_b128 v[174:177], v0 offset:128
	ds_read_b128 v[190:193], v0 offset:160
	ds_read_b128 v[194:197], v0 offset:192
	ds_read_b128 v[198:201], v0 offset:224
	s_waitcnt vmcnt(7) lgkmcnt(7)
	v_mfma_f32_32x32x16_bf16 v[80:95], v[2:5], v[104:107], 0
	s_waitcnt vmcnt(6) lgkmcnt(6)
	v_mfma_f32_32x32x16_bf16 v[80:95], v[6:9], v[108:111], v[80:95]
	s_waitcnt vmcnt(5) lgkmcnt(5)
	v_mfma_f32_32x32x16_bf16 v[80:95], v[10:13], v[112:115], v[80:95]
	s_waitcnt vmcnt(4) lgkmcnt(4)
	v_mfma_f32_32x32x16_bf16 v[80:95], v[170:173], v[120:123], v[80:95]
	s_waitcnt vmcnt(3) lgkmcnt(3)
	v_mfma_f32_32x32x16_bf16 v[80:95], v[174:177], v[124:127], v[80:95]
	s_lshl_b32 s62, s13, 1
	v_add_u32_e32 v10, 27, v165
	s_add_i32 s62, s62, s61
	v_cmp_gt_u32_e32 vcc, s42, v10
	s_movk_i32 s61, 0xff7f
	v_add_u32_e32 v11, 25, v165
	v_add_u32_e32 v12, 24, v165
	s_waitcnt vmcnt(2) lgkmcnt(2)
	v_mfma_f32_32x32x16_bf16 v[80:95], v[190:193], v[132:135], v[80:95]
	v_add_u32_e32 v13, 19, v165
	v_add_u32_e32 v14, 18, v165
	v_add_u32_e32 v175, 17, v165
	v_add_u32_e32 v176, 16, v165
	v_add_u32_e32 v10, 11, v165
	v_lshlrev_b32_e32 v0, 1, v155
	v_add3_u32 v0, s62, v164, v0
	s_waitcnt vmcnt(1) lgkmcnt(1)
	v_mfma_f32_32x32x16_bf16 v[80:95], v[194:197], v[136:139], v[80:95]
	v_add_u32_e32 v169, 0x4000, v0
	v_add_u32_e32 v15, 0x5000, v0
	ds_read2_b64 v[2:5], v169 offset0:128 offset1:130
	ds_read2_b64 v[6:9], v15 offset0:160 offset1:162
	s_waitcnt vmcnt(0) lgkmcnt(2)
	v_mfma_f32_32x32x16_bf16 v[80:95], v[198:201], v[140:143], v[80:95]
	s_nop 11
	v_cndmask_b32_e32 v170, v225, v80, vcc
	v_cmp_lt_u32_e32 vcc, s61, v166
	s_nop 1
	v_cndmask_b32_e32 v172, v225, v81, vcc
	v_cmp_gt_u32_e32 vcc, s42, v11
	s_nop 1
	v_cndmask_b32_e32 v173, v225, v82, vcc
	v_cmp_gt_u32_e32 vcc, s42, v12
	v_max_f32_e32 v11, v173, v173
	s_nop 0
	v_cndmask_b32_e32 v174, v225, v83, vcc
	v_cmp_gt_u32_e32 vcc, s42, v13
	s_nop 1
	v_cndmask_b32_e32 v171, v225, v84, vcc
	v_cmp_gt_u32_e32 vcc, s42, v14
	v_max_f32_e32 v12, v171, v171
	s_nop 0
	v_cndmask_b32_e32 v85, v225, v85, vcc
	v_cmp_gt_u32_e32 vcc, s42, v175
	s_nop 1
	v_cndmask_b32_e32 v177, v225, v86, vcc
	v_cmp_gt_u32_e32 vcc, s42, v176
	v_max_f32_e32 v13, v177, v177
	s_nop 0
	v_cndmask_b32_e32 v176, v225, v87, vcc
	v_cmp_gt_u32_e32 vcc, s42, v10
	v_add_u32_e32 v10, 10, v165
	s_nop 0
	v_cndmask_b32_e32 v175, v225, v88, vcc
	v_cmp_gt_u32_e32 vcc, s42, v10
	v_add_u32_e32 v10, 9, v165
	s_nop 0
	v_cndmask_b32_e32 v89, v225, v89, vcc
	v_cmp_gt_u32_e32 vcc, s42, v10
	v_add_u32_e32 v10, 8, v165
	s_nop 0
	v_cndmask_b32_e32 v90, v225, v90, vcc
	v_cmp_gt_u32_e32 vcc, s42, v10
	v_add_u32_e32 v10, 3, v165
	s_nop 0
	v_cndmask_b32_e32 v91, v225, v91, vcc
	v_cmp_gt_u32_e32 vcc, s42, v10
	v_add_u32_e32 v10, 2, v165
	s_nop 0
	v_cndmask_b32_e32 v86, v225, v92, vcc
	v_cmp_gt_u32_e32 vcc, s42, v10
	v_add_u32_e32 v10, 1, v165
	v_add_u32_e32 v92, 0x7000, v0
	v_cndmask_b32_e32 v87, v225, v93, vcc
	v_cmp_gt_u32_e32 vcc, s42, v10
	v_max_f32_e32 v10, v174, v174
	v_max_f32_e32 v10, v11, v10
	v_max_f32_e32 v11, v85, v85
	v_max_f32_e32 v11, v12, v11
	v_max_f32_e32 v12, v176, v176
	v_max3_f32 v10, v170, v172, v10
	v_max_f32_e32 v12, v13, v12
	v_max3_f32 v10, v10, v11, v12
	v_max_f32_e32 v11, v89, v89
	v_max_f32_e32 v12, v175, v175
	v_max_f32_e32 v11, v12, v11
	v_max_f32_e32 v12, v91, v91
	v_max_f32_e32 v13, v90, v90
	v_cndmask_b32_e32 v88, v225, v94, vcc
	v_cmp_gt_u32_e32 vcc, s42, v165
	v_max_f32_e32 v12, v13, v12
	v_max3_f32 v10, v10, v11, v12
	v_cndmask_b32_e32 v84, v225, v95, vcc
	v_max_f32_e32 v11, v87, v87
	v_max_f32_e32 v12, v86, v86
	v_max_f32_e32 v11, v12, v11
	v_max_f32_e32 v12, v84, v84
	v_max_f32_e32 v13, v88, v88
	v_max_f32_e32 v12, v13, v12
	v_max3_f32 v10, v10, v11, v12
	v_and_b32_e32 v11, 64, v224
	v_mul_f32_e32 v14, 0x3e0293ee, v10
	v_xor_b32_e32 v10, 32, v224
	v_add_u32_e32 v11, 64, v11
	v_cmp_lt_i32_e32 vcc, v10, v11
	v_add_u32_e32 v93, 0x6000, v0
	ds_read2_b64 v[80:83], v93 offset0:192 offset1:194
	v_cndmask_b32_e32 v10, v224, v10, vcc
	v_lshlrev_b32_e32 v10, 2, v10
	ds_bpermute_b32 v94, v10, v14
	ds_read2_b64 v[10:13], v92 offset0:224 offset1:226
	s_waitcnt lgkmcnt(1)
	v_max_f32_e32 v0, v94, v94
	v_max_f32_e32 v94, v14, v0
	v_add_f32_e32 v0, 0x41000000, v168
	v_cmp_gt_f32_e32 vcc, v94, v0
	s_nop 1
	v_cndmask_b32_e32 v14, v168, v94, vcc
	v_sub_f32_e32 v0, v168, v14
	v_exp_f32_e32 v0, v0
	s_cbranch_vccz .LBB0_411
	v_pk_mul_f32 v[46:47], v[46:47], v[0:1] op_sel_hi:[1,0]
	v_pk_mul_f32 v[44:45], v[44:45], v[0:1] op_sel_hi:[1,0]
	v_pk_mul_f32 v[42:43], v[42:43], v[0:1] op_sel_hi:[1,0]
	v_pk_mul_f32 v[40:41], v[40:41], v[0:1] op_sel_hi:[1,0]
	v_pk_mul_f32 v[38:39], v[38:39], v[0:1] op_sel_hi:[1,0]
	v_pk_mul_f32 v[36:37], v[36:37], v[0:1] op_sel_hi:[1,0]
	v_pk_mul_f32 v[34:35], v[34:35], v[0:1] op_sel_hi:[1,0]
	v_pk_mul_f32 v[32:33], v[32:33], v[0:1] op_sel_hi:[1,0]
	v_pk_mul_f32 v[30:31], v[30:31], v[0:1] op_sel_hi:[1,0]
	v_pk_mul_f32 v[28:29], v[28:29], v[0:1] op_sel_hi:[1,0]
	v_pk_mul_f32 v[26:27], v[26:27], v[0:1] op_sel_hi:[1,0]
	v_pk_mul_f32 v[24:25], v[24:25], v[0:1] op_sel_hi:[1,0]
	v_pk_mul_f32 v[22:23], v[22:23], v[0:1] op_sel_hi:[1,0]
	v_pk_mul_f32 v[20:21], v[20:21], v[0:1] op_sel_hi:[1,0]
	v_pk_mul_f32 v[18:19], v[18:19], v[0:1] op_sel_hi:[1,0]
	v_pk_mul_f32 v[16:17], v[16:17], v[0:1] op_sel_hi:[1,0]
	v_pk_mul_f32 v[78:79], v[78:79], v[0:1] op_sel_hi:[1,0]
	v_pk_mul_f32 v[76:77], v[76:77], v[0:1] op_sel_hi:[1,0]
	v_pk_mul_f32 v[74:75], v[74:75], v[0:1] op_sel_hi:[1,0]
	v_pk_mul_f32 v[72:73], v[72:73], v[0:1] op_sel_hi:[1,0]
	v_pk_mul_f32 v[70:71], v[70:71], v[0:1] op_sel_hi:[1,0]
	v_pk_mul_f32 v[68:69], v[68:69], v[0:1] op_sel_hi:[1,0]
	v_pk_mul_f32 v[66:67], v[66:67], v[0:1] op_sel_hi:[1,0]
	v_pk_mul_f32 v[64:65], v[64:65], v[0:1] op_sel_hi:[1,0]
	v_pk_mul_f32 v[62:63], v[62:63], v[0:1] op_sel_hi:[1,0]
	v_pk_mul_f32 v[60:61], v[60:61], v[0:1] op_sel_hi:[1,0]
	v_pk_mul_f32 v[58:59], v[58:59], v[0:1] op_sel_hi:[1,0]
	v_pk_mul_f32 v[56:57], v[56:57], v[0:1] op_sel_hi:[1,0]
	v_pk_mul_f32 v[54:55], v[54:55], v[0:1] op_sel_hi:[1,0]
	v_pk_mul_f32 v[52:53], v[52:53], v[0:1] op_sel_hi:[1,0]
	v_pk_mul_f32 v[50:51], v[50:51], v[0:1] op_sel_hi:[1,0]
	v_pk_mul_f32 v[48:49], v[48:49], v[0:1] op_sel_hi:[1,0]

; __device__ __forceinline__ float fast_exp2(float x) { return __builtin_amdgcn_exp2f(x); }
; template <int DQ, int TYPE>
; __device__ __forceinline__ void attn_item(PP p, int layer, int b, int h, int qt, char* lds, const int tid_, unsigned* next_ctr, volatile XLAS unsigned* slot) {
;     ...
;             float mx = fmaxf(sacc[0], sacc[1]);
; #pragma unroll
;             for (int i = 2; i < 16; i += 2) mx = fmaxf(mx, fmaxf(sacc[i], sacc[i + 1]));
;             mx *= c;
;             mx = fmaxf(mx, __shfl_xor(mx, 32));
;             const float m_old_ = m_run;
;             const float mnew = fmaxf(m_run, mx);
;             const float alpha = fast_exp2(m_run - mnew);
;             m_run = mnew;
;             float ls = 0.f;
; #pragma unroll
;             for (int i = 0; i < 16; ++i) { sacc[i] = fast_exp2(__builtin_fmaf(sacc[i], c, -mnew)); ls += sacc[i]; }
;             l_run = l_run * alpha + ls;
;             if (__builtin_amdgcn_ballot_w64(mx > m_old_) != 0) {
; #pragma unroll
;                 for (int md = 0; md < 4; ++md) O[md] *= alpha;
;             }
.LBB0_643:
	s_nop 10
	v_max_f32_e32 v152, v69, v69
	v_max_f32_e32 v165, v68, v68
	v_max_f32_e32 v152, v165, v152
	v_max_f32_e32 v165, v71, v71
	v_max_f32_e32 v177, v70, v70
	v_max_f32_e32 v165, v177, v165
	v_max_f32_e32 v177, v73, v73
	v_max_f32_e32 v187, v72, v72
	v_max3_f32 v152, v66, v67, v152
	v_max_f32_e32 v177, v187, v177
	v_max3_f32 v152, v152, v165, v177
	v_max_f32_e32 v165, v75, v75
	v_max_f32_e32 v177, v74, v74
	v_max_f32_e32 v165, v177, v165
	v_max_f32_e32 v177, v77, v77
	v_max_f32_e32 v187, v76, v76
	v_max_f32_e32 v177, v187, v177
	v_max3_f32 v152, v152, v165, v177
	v_max_f32_e32 v165, v79, v79
	v_max_f32_e32 v177, v78, v78
	v_max_f32_e32 v165, v177, v165
	v_max_f32_e32 v177, v81, v81
	v_max_f32_e32 v187, v80, v80
	v_max_f32_e32 v177, v187, v177
	v_max3_f32 v152, v152, v165, v177
	v_and_b32_e32 v177, 64, v224
	v_xor_b32_e32 v165, 32, v224
	v_add_u32_e32 v177, 64, v177
	v_cmp_lt_i32_e32 vcc, v165, v177
	v_mul_f32_e32 v152, 0x3e0293ee, v152
	s_nop 0
	v_cndmask_b32_e32 v165, v224, v165, vcc
	v_lshlrev_b32_e32 v165, 2, v165
	ds_bpermute_b32 v165, v165, v152
	s_waitcnt lgkmcnt(0)
	v_max_f32_e32 v165, v165, v165
	v_max_f32_e32 v177, v152, v165
	v_add_f32_e32 v152, 0x41000000, v176
	v_cmp_gt_f32_e32 vcc, v177, v152
	s_nop 1
	v_cndmask_b32_e32 v165, v176, v177, vcc
	v_sub_f32_e32 v152, v176, v165
	v_exp_f32_e32 v152, v152
	s_cbranch_vccz .LBB0_645
	v_pk_mul_f32 v[32:33], v[32:33], v[152:153] op_sel_hi:[1,0]
	v_pk_mul_f32 v[30:31], v[30:31], v[152:153] op_sel_hi:[1,0]
	v_pk_mul_f32 v[28:29], v[28:29], v[152:153] op_sel_hi:[1,0]
	v_pk_mul_f32 v[26:27], v[26:27], v[152:153] op_sel_hi:[1,0]
	v_pk_mul_f32 v[24:25], v[24:25], v[152:153] op_sel_hi:[1,0]
	v_pk_mul_f32 v[22:23], v[22:23], v[152:153] op_sel_hi:[1,0]
	v_pk_mul_f32 v[20:21], v[20:21], v[152:153] op_sel_hi:[1,0]
	v_pk_mul_f32 v[18:19], v[18:19], v[152:153] op_sel_hi:[1,0]
	v_pk_mul_f32 v[16:17], v[16:17], v[152:153] op_sel_hi:[1,0]
	v_pk_mul_f32 v[14:15], v[14:15], v[152:153] op_sel_hi:[1,0]
	v_pk_mul_f32 v[12:13], v[12:13], v[152:153] op_sel_hi:[1,0]
	v_pk_mul_f32 v[10:11], v[10:11], v[152:153] op_sel_hi:[1,0]
	v_pk_mul_f32 v[8:9], v[8:9], v[152:153] op_sel_hi:[1,0]
	v_pk_mul_f32 v[6:7], v[6:7], v[152:153] op_sel_hi:[1,0]
	v_pk_mul_f32 v[4:5], v[4:5], v[152:153] op_sel_hi:[1,0]
	v_pk_mul_f32 v[2:3], v[2:3], v[152:153] op_sel_hi:[1,0]
	v_pk_mul_f32 v[64:65], v[64:65], v[152:153] op_sel_hi:[1,0]
	v_pk_mul_f32 v[62:63], v[62:63], v[152:153] op_sel_hi:[1,0]
	v_pk_mul_f32 v[60:61], v[60:61], v[152:153] op_sel_hi:[1,0]
	v_pk_mul_f32 v[58:59], v[58:59], v[152:153] op_sel_hi:[1,0]
	v_pk_mul_f32 v[56:57], v[56:57], v[152:153] op_sel_hi:[1,0]
	v_pk_mul_f32 v[54:55], v[54:55], v[152:153] op_sel_hi:[1,0]
	v_pk_mul_f32 v[52:53], v[52:53], v[152:153] op_sel_hi:[1,0]
	v_pk_mul_f32 v[50:51], v[50:51], v[152:153] op_sel_hi:[1,0]
	v_pk_mul_f32 v[48:49], v[48:49], v[152:153] op_sel_hi:[1,0]
	v_pk_mul_f32 v[46:47], v[46:47], v[152:153] op_sel_hi:[1,0]
	v_pk_mul_f32 v[44:45], v[44:45], v[152:153] op_sel_hi:[1,0]
	v_pk_mul_f32 v[42:43], v[42:43], v[152:153] op_sel_hi:[1,0]
	v_pk_mul_f32 v[40:41], v[40:41], v[152:153] op_sel_hi:[1,0]
	v_pk_mul_f32 v[38:39], v[38:39], v[152:153] op_sel_hi:[1,0]
	v_pk_mul_f32 v[36:37], v[36:37], v[152:153] op_sel_hi:[1,0]
	v_pk_mul_f32 v[34:35], v[34:35], v[152:153] op_sel_hi:[1,0]

; __device__ __forceinline__ float fast_exp2(float x) { return __builtin_amdgcn_exp2f(x); }
; template <int DQ, int TYPE>
; __device__ __forceinline__ void attn_item(PP p, int layer, int b, int h, int qt, char* lds, const int tid_, unsigned* next_ctr, volatile XLAS unsigned* slot) {
;     ...
;             float mx = fmaxf(sacc[0], sacc[1]);
; #pragma unroll
;             for (int i = 2; i < 16; i += 2) mx = fmaxf(mx, fmaxf(sacc[i], sacc[i + 1]));
;             mx *= c;
;             mx = fmaxf(mx, __shfl_xor(mx, 32));
;             const float m_old_ = m_run;
;             const float mnew = fmaxf(m_run, mx);
;             const float alpha = fast_exp2(m_run - mnew);
;             m_run = mnew;
;             float ls = 0.f;
; #pragma unroll
;             for (int i = 0; i < 16; ++i) { sacc[i] = fast_exp2(__builtin_fmaf(sacc[i], c, -mnew)); ls += sacc[i]; }
;             l_run = l_run * alpha + ls;
;             if (__builtin_amdgcn_ballot_w64(mx > m_old_) != 0) {
; #pragma unroll
;                 for (int md = 0; md < 4; ++md) O[md] *= alpha;
;             }
.LBB0_667:
	s_nop 10
	v_max_f32_e32 v192, v69, v69
	v_max_f32_e32 v200, v68, v68
	v_max_f32_e32 v192, v200, v192
	v_max_f32_e32 v200, v71, v71
	v_max_f32_e32 v206, v70, v70
	v_max_f32_e32 v200, v206, v200
	v_max_f32_e32 v206, v73, v73
	v_max_f32_e32 v207, v72, v72
	v_max3_f32 v192, v66, v67, v192
	v_max_f32_e32 v206, v207, v206
	v_max3_f32 v192, v192, v200, v206
	v_max_f32_e32 v200, v75, v75
	v_max_f32_e32 v206, v74, v74
	v_max_f32_e32 v200, v206, v200
	v_max_f32_e32 v206, v77, v77
	v_max_f32_e32 v207, v76, v76
	v_max_f32_e32 v206, v207, v206
	v_max3_f32 v192, v192, v200, v206
	v_max_f32_e32 v200, v79, v79
	v_max_f32_e32 v206, v78, v78
	v_max_f32_e32 v200, v206, v200
	v_max_f32_e32 v206, v81, v81
	v_max_f32_e32 v207, v80, v80
	v_max_f32_e32 v206, v207, v206
	v_max3_f32 v192, v192, v200, v206
	v_and_b32_e32 v206, 64, v224
	v_xor_b32_e32 v200, 32, v224
	v_add_u32_e32 v206, 64, v206
	v_cmp_lt_i32_e32 vcc, v200, v206
	v_mul_f32_e32 v192, 0x3dd53b94, v192
	s_nop 0
	v_cndmask_b32_e32 v200, v224, v200, vcc
	v_lshlrev_b32_e32 v200, 2, v200
	ds_bpermute_b32 v200, v200, v192
	s_waitcnt lgkmcnt(0)
	v_max_f32_e32 v200, v200, v200
	v_max_f32_e32 v206, v192, v200
	v_add_f32_e32 v192, 0x41000000, v205
	v_cmp_gt_f32_e32 vcc, v206, v192
	s_nop 1
	v_cndmask_b32_e32 v200, v205, v206, vcc
	v_sub_f32_e32 v192, v205, v200
	v_exp_f32_e32 v192, v192
	s_cbranch_vccz .LBB0_669
	v_pk_mul_f32 v[32:33], v[32:33], v[192:193] op_sel_hi:[1,0]
	v_pk_mul_f32 v[30:31], v[30:31], v[192:193] op_sel_hi:[1,0]
	v_pk_mul_f32 v[28:29], v[28:29], v[192:193] op_sel_hi:[1,0]
	v_pk_mul_f32 v[26:27], v[26:27], v[192:193] op_sel_hi:[1,0]
	v_pk_mul_f32 v[24:25], v[24:25], v[192:193] op_sel_hi:[1,0]
	v_pk_mul_f32 v[22:23], v[22:23], v[192:193] op_sel_hi:[1,0]
	v_pk_mul_f32 v[20:21], v[20:21], v[192:193] op_sel_hi:[1,0]
	v_pk_mul_f32 v[18:19], v[18:19], v[192:193] op_sel_hi:[1,0]
	v_pk_mul_f32 v[16:17], v[16:17], v[192:193] op_sel_hi:[1,0]
	v_pk_mul_f32 v[14:15], v[14:15], v[192:193] op_sel_hi:[1,0]
	v_pk_mul_f32 v[12:13], v[12:13], v[192:193] op_sel_hi:[1,0]
	v_pk_mul_f32 v[10:11], v[10:11], v[192:193] op_sel_hi:[1,0]
	v_pk_mul_f32 v[8:9], v[8:9], v[192:193] op_sel_hi:[1,0]
	v_pk_mul_f32 v[6:7], v[6:7], v[192:193] op_sel_hi:[1,0]
	v_pk_mul_f32 v[4:5], v[4:5], v[192:193] op_sel_hi:[1,0]
	v_pk_mul_f32 v[2:3], v[2:3], v[192:193] op_sel_hi:[1,0]
	v_pk_mul_f32 v[64:65], v[64:65], v[192:193] op_sel_hi:[1,0]
	v_pk_mul_f32 v[62:63], v[62:63], v[192:193] op_sel_hi:[1,0]
	v_pk_mul_f32 v[60:61], v[60:61], v[192:193] op_sel_hi:[1,0]
	v_pk_mul_f32 v[58:59], v[58:59], v[192:193] op_sel_hi:[1,0]
	v_pk_mul_f32 v[56:57], v[56:57], v[192:193] op_sel_hi:[1,0]
	v_pk_mul_f32 v[54:55], v[54:55], v[192:193] op_sel_hi:[1,0]
	v_pk_mul_f32 v[52:53], v[52:53], v[192:193] op_sel_hi:[1,0]
	v_pk_mul_f32 v[50:51], v[50:51], v[192:193] op_sel_hi:[1,0]
	v_pk_mul_f32 v[48:49], v[48:49], v[192:193] op_sel_hi:[1,0]
	v_pk_mul_f32 v[46:47], v[46:47], v[192:193] op_sel_hi:[1,0]
	v_pk_mul_f32 v[44:45], v[44:45], v[192:193] op_sel_hi:[1,0]
	v_pk_mul_f32 v[42:43], v[42:43], v[192:193] op_sel_hi:[1,0]
	v_pk_mul_f32 v[40:41], v[40:41], v[192:193] op_sel_hi:[1,0]
	v_pk_mul_f32 v[38:39], v[38:39], v[192:193] op_sel_hi:[1,0]
	v_pk_mul_f32 v[36:37], v[36:37], v[192:193] op_sel_hi:[1,0]
	v_pk_mul_f32 v[34:35], v[34:35], v[192:193] op_sel_hi:[1,0]
